# static s_setprio 1 for waves 4-7 during the prompt-attention tile loop (reset to 0 at loop exit)
# baseline (speedup 1.0000x reference)
; __device__ __forceinline__ void attn_unit(const AttnJob& J, LAS unsigned char* lds) {
;     ...
;     for (int t = 0; t < J.NT; t += 2) {
;         attn_stage(lds, 0, kA, vA);
;         __syncthreads();
;         if (t + 2 < J.NT) attn_load(J, t + 2, kA, vA);
;         if (active && 64 * t <= qlo + 31) attn_tile(t, 0, lds, qr, cq2, qlo, qpos, q32, hi, mrun, lrun, o0, o1);
;         if (t + 1 < J.NT) {
;             attn_stage(lds, 1, kB, vB);
;             __syncthreads();
;             if (t + 3 < J.NT) attn_load(J, t + 3, kB, vB);
;             if (active && 64 * (t + 1) <= qlo + 31) attn_tile(t + 1, 1, lds, qr, cq2, qlo, qpos, q32, hi, mrun, lrun, o0, o1);
;         }
;     }
.LBB0_645:
	s_bfe_u32 s6, s21, 0x30005
	s_cmp_ge_u32 s6, 4
	s_cbranch_scc0 .Lprio_skip
	s_setprio 1

; __device__ __forceinline__ void attn_tile(int t, int buf, LAS unsigned char* lds, const bf16x8 (&qr)[4], float cq2, int qlo, int qpos, int q32, int hi,
;                                           float& mrun, float& lrun, f32x16& o0, f32x16& o1) {
;     ...
;     f32x2 ls2 = (f32x2){0.f, 0.f};
; #pragma unroll
;     for (int r = 0; r < 16; r += 2) {
;         const f32x2 d0 = (f32x2){s0[r], s0[r + 1]} - mnew, d1 = (f32x2){s1[r], s1[r + 1]} - mnew;
;         f32x2 e0, e1; e0.x = fexp2(d0.x); e0.y = fexp2(d0.y); e1.x = fexp2(d1.x); e1.y = fexp2(d1.y);
;         s0[r] = e0.x; s0[r + 1] = e0.y; s1[r] = e1.x; s1[r + 1] = e1.y;
;         ls2 += e0 + e1;
;     }
;     lrun += ls2.x + ls2.y;
; #pragma unroll
;     for (int p = 0; p < 2; ++p)
; #pragma unroll
;         for (int sx = 0; sx < 2; ++sx) {
;             u32x4 pw;
;             if (p == 0) pw = (u32x4){pk_bf16(s0[8 * sx + 0], s0[8 * sx + 1]), pk_bf16(s0[8 * sx + 2], s0[8 * sx + 3]), pk_bf16(s0[8 * sx + 4], s0[8 * sx + 5]), pk_bf16(s0[8 * sx + 6], s0[8 * sx + 7])};
;             else        pw = (u32x4){pk_bf16(s1[8 * sx + 0], s1[8 * sx + 1]), pk_bf16(s1[8 * sx + 2], s1[8 * sx + 3]), pk_bf16(s1[8 * sx + 4], s1[8 * sx + 5]), pk_bf16(s1[8 * sx + 6], s1[8 * sx + 7])};
;             const bf16x8 pf = __builtin_bit_cast(bf16x8, pw);
;             const int ko = (32 * p + 16 * sx + 4 * hi) * 2;
;             const u32x2 a0 = *(const LAS u32x2*)(Vt + q32 * 136 + ko), a1 = *(const LAS u32x2*)(Vt + q32 * 136 + ko + 16);
;             const u32x2 b0 = *(const LAS u32x2*)(Vt + (32 + q32) * 136 + ko), b1 = *(const LAS u32x2*)(Vt + (32 + q32) * 136 + ko + 16);
;             const bf16x8 vf0 = __builtin_bit_cast(bf16x8, (u32x4){a0.x, a0.y, a1.x, a1.y});
;             const bf16x8 vf1 = __builtin_bit_cast(bf16x8, (u32x4){b0.x, b0.y, b1.x, b1.y});
;             o0 = __builtin_amdgcn_mfma_f32_32x32x16_bf16(vf0, pf, o0, 0, 0, 0);
;             o1 = __builtin_amdgcn_mfma_f32_32x32x16_bf16(vf1, pf, o1, 0, 0, 0);
;         }
; }
; __device__ __forceinline__ void attn_unit(const AttnJob& J, LAS unsigned char* lds) {
;     const int tid = fresh_tid(), lane = tid & 63, q32 = lane & 31, hi = lane >> 5; const int wid = __builtin_amdgcn_readfirstlane(tid >> 6);
;     const LAS float* c2s = (const LAS float*)(lds + AT_C2);
;     const bool active = wid < J.nqw;
;     const int qlo = J.qpos0 + 32 * wid, qpos = qlo + q32;
.Lend_O:
	s_add_i32 s22, s22, 2
	v_add_u32_e32 v111, 0x200, v111
	s_cmp_lt_u32 s22, s20
	s_cbranch_scc1 .Lslot_E
	s_waitcnt vmcnt(0)
	ds_write_b16 v157, v94 offset:35584
	ds_write_b16_d16_hi v157, v94 offset:35720
	ds_write_b16 v157, v95 offset:35856
	ds_write_b16_d16_hi v157, v95 offset:35992
	ds_write_b16 v157, v96 offset:36128
	ds_write_b16_d16_hi v157, v96 offset:36264
	ds_write_b16 v157, v97 offset:36400
	ds_write_b16_d16_hi v157, v97 offset:36536
	s_waitcnt lgkmcnt(0)
	s_barrier
	s_setprio 0
	s_cmp_eq_u32 s27, 0
	s_cbranch_scc1 .LBB0_663
	v_add_u32_e32 v122, 0x8800, v113
	v_add_u32_e32 v123, 0x9800, v113
	ds_read2_b64 v[166:169], v122 offset0:96 offset1:98
	ds_read2_b64 v[170:173], v123 offset0:128 offset1:130
	ds_read2_b64 v[174:177], v122 offset0:100 offset1:102
	ds_read2_b64 v[178:181], v123 offset0:132 offset1:134
	ds_read2_b64 v[182:185], v122 offset0:104 offset1:106
	ds_read2_b64 v[186:189], v123 offset0:136 offset1:138
	ds_read2_b64 v[190:193], v122 offset0:108 offset1:110
	ds_read2_b64 v[194:197], v123 offset0:140 offset1:142
	v_sub_f32_e32 v206, v206, v114
	v_sub_f32_e32 v207, v207, v114
	v_sub_f32_e32 v208, v208, v114
	v_sub_f32_e32 v209, v209, v114
	v_sub_f32_e32 v210, v210, v114
	v_sub_f32_e32 v211, v211, v114
	v_sub_f32_e32 v212, v212, v114
	v_sub_f32_e32 v213, v213, v114
	v_exp_f32_e32 v206, v206
	v_exp_f32_e32 v207, v207
	v_exp_f32_e32 v208, v208
	v_exp_f32_e32 v209, v209
	v_exp_f32_e32 v210, v210
	v_exp_f32_e32 v211, v211
	v_exp_f32_e32 v212, v212
	v_exp_f32_e32 v213, v213
	v_cvt_pk_bf16_f32 v118, v206, v207
	v_cvt_pk_bf16_f32 v119, v208, v209
	v_cvt_pk_bf16_f32 v120, v210, v211
	v_cvt_pk_bf16_f32 v121, v212, v213
	v_add_f32_e32 v116, v206, v208
	v_add_f32_e32 v117, v207, v209
	v_add_f32_e32 v116, v116, v210
	v_add_f32_e32 v117, v117, v211
	v_add_f32_e32 v116, v116, v212
	v_add_f32_e32 v117, v117, v213
	s_waitcnt lgkmcnt(0)
	v_mfma_f32_32x32x16_bf16 v[18:33], v[166:169], v[118:121], v[18:33]
	v_mfma_f32_32x32x16_bf16 v[2:17], v[170:173], v[118:121], v[2:17]
	v_sub_f32_e32 v214, v214, v114
	v_sub_f32_e32 v215, v215, v114
	v_sub_f32_e32 v216, v216, v114
	v_sub_f32_e32 v217, v217, v114
	v_sub_f32_e32 v218, v218, v114
	v_sub_f32_e32 v219, v219, v114
	v_sub_f32_e32 v220, v220, v114
	v_sub_f32_e32 v221, v221, v114
	v_exp_f32_e32 v214, v214
	v_exp_f32_e32 v215, v215
	v_exp_f32_e32 v216, v216
	v_exp_f32_e32 v217, v217
	v_exp_f32_e32 v218, v218
	v_exp_f32_e32 v219, v219
	v_exp_f32_e32 v220, v220
	v_exp_f32_e32 v221, v221
	v_cvt_pk_bf16_f32 v118, v214, v215
	v_cvt_pk_bf16_f32 v119, v216, v217
	v_cvt_pk_bf16_f32 v120, v218, v219
	v_cvt_pk_bf16_f32 v121, v220, v221
	v_add_f32_e32 v116, v116, v214
	v_add_f32_e32 v117, v117, v215
	v_add_f32_e32 v116, v116, v216
	v_add_f32_e32 v117, v117, v217
	v_add_f32_e32 v116, v116, v218
	v_add_f32_e32 v117, v117, v219
	v_add_f32_e32 v116, v116, v220
	v_add_f32_e32 v117, v117, v221
	v_mfma_f32_32x32x16_bf16 v[18:33], v[174:177], v[118:121], v[18:33]
	v_mfma_f32_32x32x16_bf16 v[2:17], v[178:181], v[118:121], v[2:17]
	v_sub_f32_e32 v222, v222, v114
	v_sub_f32_e32 v223, v223, v114
	v_sub_f32_e32 v224, v224, v114
	v_sub_f32_e32 v225, v225, v114
	v_sub_f32_e32 v226, v226, v114
	v_sub_f32_e32 v227, v227, v114
	v_sub_f32_e32 v228, v228, v114
	v_sub_f32_e32 v229, v229, v114
	v_exp_f32_e32 v222, v222
	v_exp_f32_e32 v223, v223
	v_exp_f32_e32 v224, v224
	v_exp_f32_e32 v225, v225
	v_exp_f32_e32 v226, v226
	v_exp_f32_e32 v227, v227
	v_exp_f32_e32 v228, v228
	v_exp_f32_e32 v229, v229
	v_cvt_pk_bf16_f32 v118, v222, v223
	v_cvt_pk_bf16_f32 v119, v224, v225
	v_cvt_pk_bf16_f32 v120, v226, v227
	v_cvt_pk_bf16_f32 v121, v228, v229
	v_add_f32_e32 v116, v116, v222
	v_add_f32_e32 v117, v117, v223
	v_add_f32_e32 v116, v116, v224
	v_add_f32_e32 v117, v117, v225
	v_add_f32_e32 v116, v116, v226
	v_add_f32_e32 v117, v117, v227
	v_add_f32_e32 v116, v116, v228
	v_add_f32_e32 v117, v117, v229
	v_mfma_f32_32x32x16_bf16 v[18:33], v[182:185], v[118:121], v[18:33]
	v_mfma_f32_32x32x16_bf16 v[2:17], v[186:189], v[118:121], v[2:17]
	v_sub_f32_e32 v230, v230, v114
	v_sub_f32_e32 v231, v231, v114
	v_sub_f32_e32 v232, v232, v114
	v_sub_f32_e32 v233, v233, v114
	v_sub_f32_e32 v234, v234, v114
	v_sub_f32_e32 v235, v235, v114
	v_sub_f32_e32 v236, v236, v114
	v_sub_f32_e32 v237, v237, v114
	v_exp_f32_e32 v230, v230
	v_exp_f32_e32 v231, v231
	v_exp_f32_e32 v232, v232
	v_exp_f32_e32 v233, v233
	v_exp_f32_e32 v234, v234
	v_exp_f32_e32 v235, v235
	v_exp_f32_e32 v236, v236
	v_exp_f32_e32 v237, v237
	v_cvt_pk_bf16_f32 v118, v230, v231
	v_cvt_pk_bf16_f32 v119, v232, v233
	v_cvt_pk_bf16_f32 v120, v234, v235
	v_cvt_pk_bf16_f32 v121, v236, v237
	v_add_f32_e32 v116, v116, v230
	v_add_f32_e32 v117, v117, v231
	v_add_f32_e32 v116, v116, v232
	v_add_f32_e32 v117, v117, v233
	v_add_f32_e32 v116, v116, v234
	v_add_f32_e32 v117, v117, v235
	v_add_f32_e32 v116, v116, v236
	v_add_f32_e32 v117, v117, v237
	v_mfma_f32_32x32x16_bf16 v[18:33], v[190:193], v[118:121], v[18:33]
	v_mfma_f32_32x32x16_bf16 v[2:17], v[194:197], v[118:121], v[2:17]
	v_add_f32_e32 v116, v116, v117
	v_add_f32_e32 v109, v109, v116
